# scan carry chains: 32 loads batched per 16-step block; out_proj L0 fp32 A-path loads batched
# speedup vs baseline: 1.0046x; 1.0046x over previous
.LBB0_511:
	v_lshl_add_u64 v[4:5], s[2:3], 0, v[0:1]
	v_lshl_add_u64 v[2:3], s[0:1], 0, v[0:1]
	global_load_dword v182, v[4:5], off offset:3072
	global_load_dword v183, v[2:3], off offset:3072
	s_add_i32 s5, s5, -16
	s_add_u32 s0, s0, 0xfffe8000
	s_addc_u32 s1, s1, -1
	s_add_u32 s2, s2, 0xfffe8000
	s_addc_u32 s3, s3, -1
	s_cmp_gt_i32 s5, s88
	global_load_dword v184, v[4:5], off offset:-3072
	global_load_dword v185, v[2:3], off offset:-3072
	v_add_co_u32_e32 v6, vcc, 0xffffe000, v4
	s_nop 1
	v_addc_co_u32_e32 v7, vcc, -1, v5, vcc
	global_load_dword v186, v[6:7], off offset:-1024
	v_add_co_u32_e32 v6, vcc, 0xffffe000, v2
	s_nop 1
	v_addc_co_u32_e32 v7, vcc, -1, v3, vcc
	global_load_dword v187, v[6:7], off offset:-1024
	v_add_co_u32_e32 v6, vcc, 0xffffd000, v4
	s_nop 1
	v_addc_co_u32_e32 v7, vcc, -1, v5, vcc
	global_load_dword v188, v[6:7], off offset:-3072
	v_add_co_u32_e32 v6, vcc, 0xffffd000, v2
	s_nop 1
	v_addc_co_u32_e32 v7, vcc, -1, v3, vcc
	global_load_dword v189, v[6:7], off offset:-3072
	v_add_co_u32_e32 v6, vcc, 0xffffb000, v4
	s_nop 1
	v_addc_co_u32_e32 v7, vcc, -1, v5, vcc
	global_load_dword v190, v[6:7], off offset:-1024
	v_add_co_u32_e32 v6, vcc, 0xffffb000, v2
	s_nop 1
	v_addc_co_u32_e32 v7, vcc, -1, v3, vcc
	global_load_dword v191, v[6:7], off offset:-1024
	v_add_co_u32_e32 v6, vcc, s10, v4
	s_nop 1
	v_addc_co_u32_e32 v7, vcc, -1, v5, vcc
	global_load_dword v192, v[6:7], off offset:-3072
	v_add_co_u32_e32 v6, vcc, s10, v2
	s_nop 1
	v_addc_co_u32_e32 v7, vcc, -1, v3, vcc
	global_load_dword v193, v[6:7], off offset:-3072
	v_add_co_u32_e32 v6, vcc, 0xffff8000, v4
	s_nop 1
	v_addc_co_u32_e32 v7, vcc, -1, v5, vcc
	global_load_dword v194, v[6:7], off offset:-1024
	v_add_co_u32_e32 v6, vcc, 0xffff8000, v2
	s_nop 1
	v_addc_co_u32_e32 v7, vcc, -1, v3, vcc
	global_load_dword v195, v[6:7], off offset:-1024
	v_add_co_u32_e32 v6, vcc, 0xffff7000, v4
	s_nop 1
	v_addc_co_u32_e32 v7, vcc, -1, v5, vcc
	global_load_dword v196, v[6:7], off offset:-3072
	v_add_co_u32_e32 v6, vcc, 0xffff7000, v2
	s_nop 1
	v_addc_co_u32_e32 v7, vcc, -1, v3, vcc
	global_load_dword v197, v[6:7], off offset:-3072
	v_add_co_u32_e32 v6, vcc, 0xffff5000, v4
	s_nop 1
	v_addc_co_u32_e32 v7, vcc, -1, v5, vcc
	global_load_dword v198, v[6:7], off offset:-1024
	v_add_co_u32_e32 v6, vcc, 0xffff5000, v2
	s_nop 1
	v_addc_co_u32_e32 v7, vcc, -1, v3, vcc
	global_load_dword v199, v[6:7], off offset:-1024
	v_add_co_u32_e32 v6, vcc, 0xffff4000, v4
	s_nop 1
	v_addc_co_u32_e32 v7, vcc, -1, v5, vcc
	global_load_dword v200, v[6:7], off offset:-3072
	v_add_co_u32_e32 v6, vcc, 0xffff4000, v2
	s_nop 1
	v_addc_co_u32_e32 v7, vcc, -1, v3, vcc
	global_load_dword v201, v[6:7], off offset:-3072
	v_add_co_u32_e32 v6, vcc, 0xffff2000, v4
	s_nop 1
	v_addc_co_u32_e32 v7, vcc, -1, v5, vcc
	global_load_dword v202, v[6:7], off offset:-1024
	v_add_co_u32_e32 v6, vcc, 0xffff2000, v2
	s_nop 1
	v_addc_co_u32_e32 v7, vcc, -1, v3, vcc
	global_load_dword v203, v[6:7], off offset:-1024
	v_add_co_u32_e32 v6, vcc, 0xffff1000, v4
	s_nop 1
	v_addc_co_u32_e32 v7, vcc, -1, v5, vcc
	global_load_dword v204, v[6:7], off offset:-3072
	v_add_co_u32_e32 v6, vcc, 0xffff1000, v2
	s_nop 1
	v_addc_co_u32_e32 v7, vcc, -1, v3, vcc
	global_load_dword v205, v[6:7], off offset:-3072
	v_add_co_u32_e32 v6, vcc, 0xfffef000, v4
	s_nop 1
	v_addc_co_u32_e32 v7, vcc, -1, v5, vcc
	global_load_dword v206, v[6:7], off offset:-1024
	v_add_co_u32_e32 v6, vcc, 0xfffef000, v2
	s_nop 1
	v_addc_co_u32_e32 v7, vcc, -1, v3, vcc
	global_load_dword v207, v[6:7], off offset:-1024
	v_add_co_u32_e32 v6, vcc, 0xfffee000, v4
	s_nop 1
	v_addc_co_u32_e32 v7, vcc, -1, v5, vcc
	global_load_dword v208, v[6:7], off offset:-3072
	v_add_co_u32_e32 v6, vcc, 0xfffee000, v2
	s_nop 1
	v_addc_co_u32_e32 v7, vcc, -1, v3, vcc
	global_load_dword v209, v[6:7], off offset:-3072
	v_add_co_u32_e32 v6, vcc, 0xfffec000, v4
	s_nop 1
	v_addc_co_u32_e32 v7, vcc, -1, v5, vcc
	global_load_dword v210, v[6:7], off offset:-1024
	v_add_co_u32_e32 v6, vcc, 0xfffec000, v2
	s_nop 1
	v_addc_co_u32_e32 v7, vcc, -1, v3, vcc
	v_add_co_u32_e32 v4, vcc, 0xfffeb000, v4
	global_load_dword v211, v[6:7], off offset:-1024
	s_nop 0
	v_addc_co_u32_e32 v5, vcc, -1, v5, vcc
	v_add_co_u32_e32 v2, vcc, 0xfffeb000, v2
	global_load_dword v212, v[4:5], off offset:-3072
	s_nop 0
	v_addc_co_u32_e32 v3, vcc, -1, v3, vcc
	global_load_dword v213, v[2:3], off offset:-3072
	s_waitcnt vmcnt(0)
	v_fmac_f32_e32 v183, v77, v182
	v_fmac_f32_e32 v185, v183, v184
	v_fmac_f32_e32 v187, v185, v186
	v_fmac_f32_e32 v189, v187, v188
	v_fmac_f32_e32 v191, v189, v190
	v_fmac_f32_e32 v193, v191, v192
	v_fmac_f32_e32 v195, v193, v194
	v_fmac_f32_e32 v197, v195, v196
	v_fmac_f32_e32 v199, v197, v198
	v_fmac_f32_e32 v201, v199, v200
	v_fmac_f32_e32 v203, v201, v202
	v_fmac_f32_e32 v205, v203, v204
	v_fmac_f32_e32 v207, v205, v206
	v_fmac_f32_e32 v209, v207, v208
	v_fmac_f32_e32 v211, v209, v210
	v_fmac_f32_e32 v213, v211, v212
	v_mov_b32_e32 v77, v213
	s_cbranch_scc1 .LBB0_511
	s_movk_i32 s52, 0xa000

.LBB0_521:
	v_lshl_add_u64 v[2:3], s[66:67], 0, v[0:1]
	global_load_dword v182, v[2:3], off
	v_lshl_add_u64 v[2:3], s[68:69], 0, v[0:1]
	global_load_dword v183, v[2:3], off
	v_lshl_add_u64 v[2:3], s[64:65], 0, v[0:1]
	s_add_i32 s5, s5, 16
	global_load_dword v184, v[2:3], off
	v_lshl_add_u64 v[2:3], s[62:63], 0, v[0:1]
	global_load_dword v185, v[2:3], off
	v_lshl_add_u64 v[2:3], s[60:61], 0, v[0:1]
	global_load_dword v186, v[2:3], off
	v_lshl_add_u64 v[2:3], s[58:59], 0, v[0:1]
	global_load_dword v187, v[2:3], off
	v_lshl_add_u64 v[2:3], s[56:57], 0, v[0:1]
	global_load_dword v188, v[2:3], off
	v_lshl_add_u64 v[2:3], s[24:25], 0, v[0:1]
	global_load_dword v189, v[2:3], off
	v_lshl_add_u64 v[2:3], s[0:1], 0, v[0:1]
	global_load_dword v190, v[2:3], off
	v_lshl_add_u64 v[2:3], s[22:23], 0, v[0:1]
	global_load_dword v191, v[2:3], off
	v_lshl_add_u64 v[2:3], s[2:3], 0, v[0:1]
	global_load_dword v192, v[2:3], off
	v_lshl_add_u64 v[2:3], s[20:21], 0, v[0:1]
	global_load_dword v193, v[2:3], off
	v_lshl_add_u64 v[2:3], s[16:17], 0, v[0:1]
	global_load_dword v194, v[2:3], off
	v_lshl_add_u64 v[2:3], s[14:15], 0, v[0:1]
	global_load_dword v195, v[2:3], off
	v_lshl_add_u64 v[2:3], s[12:13], 0, v[0:1]
	global_load_dword v196, v[2:3], off
	v_lshl_add_u64 v[2:3], s[80:81], 0, v[0:1]
	global_load_dword v197, v[2:3], off
	v_lshl_add_u64 v[2:3], s[78:79], 0, v[0:1]
	global_load_dword v198, v[2:3], off
	v_lshl_add_u64 v[2:3], s[76:77], 0, v[0:1]
	global_load_dword v199, v[2:3], off
	v_lshl_add_u64 v[2:3], s[10:11], 0, v[0:1]
	global_load_dword v200, v[2:3], off
	v_lshl_add_u64 v[2:3], s[18:19], 0, v[0:1]
	global_load_dword v201, v[2:3], off
	v_lshl_add_u64 v[2:3], s[8:9], 0, v[0:1]
	global_load_dword v202, v[2:3], off
	v_lshl_add_u64 v[2:3], s[38:39], 0, v[0:1]
	global_load_dword v203, v[2:3], off
	v_lshl_add_u64 v[2:3], vcc, 0, v[0:1]
	global_load_dword v204, v[2:3], off
	v_lshl_add_u64 v[2:3], s[96:97], 0, v[0:1]
	global_load_dword v205, v[2:3], off
	v_lshl_add_u64 v[2:3], s[86:87], 0, v[0:1]
	global_load_dword v206, v[2:3], off
	v_lshl_add_u64 v[2:3], s[84:85], 0, v[0:1]
	global_load_dword v207, v[2:3], off
	v_lshl_add_u64 v[2:3], s[82:83], 0, v[0:1]
	global_load_dword v208, v[2:3], off
	v_lshl_add_u64 v[2:3], s[48:49], 0, v[0:1]
	global_load_dword v209, v[2:3], off
	v_lshl_add_u64 v[2:3], s[36:37], 0, v[0:1]
	global_load_dword v210, v[2:3], off
	v_lshl_add_u64 v[2:3], s[34:35], 0, v[0:1]
	global_load_dword v211, v[2:3], off
	v_lshl_add_u64 v[2:3], s[30:31], 0, v[0:1]
	global_load_dword v212, v[2:3], off
	v_lshl_add_u64 v[2:3], s[28:29], 0, v[0:1]
	global_load_dword v213, v[2:3], off
	s_add_u32 s28, s28, 0x18000
	s_addc_u32 s29, s29, 0
	s_add_u32 s30, s30, 0x18000
	s_addc_u32 s31, s31, 0
	s_add_u32 s34, s34, 0x18000
	s_addc_u32 s35, s35, 0
	s_add_u32 s36, s36, 0x18000
	s_addc_u32 s37, s37, 0
	s_add_u32 s48, s48, 0x18000
	s_addc_u32 s49, s49, 0
	s_add_u32 s82, s82, 0x18000
	s_addc_u32 s83, s83, 0
	s_add_u32 s84, s84, 0x18000
	s_addc_u32 s85, s85, 0
	s_add_u32 s86, s86, 0x18000
	s_addc_u32 s87, s87, 0
	s_add_u32 s96, s96, 0x18000
	s_addc_u32 s97, s97, 0
	s_add_u32 vcc_lo, vcc_lo, 0x18000
	s_addc_u32 vcc_hi, vcc_hi, 0
	s_add_u32 s38, s38, 0x18000
	s_addc_u32 s39, s39, 0
	s_add_u32 s8, s8, 0x18000
	s_addc_u32 s9, s9, 0
	s_add_u32 s18, s18, 0x18000
	s_addc_u32 s19, s19, 0
	s_add_u32 s10, s10, 0x18000
	s_addc_u32 s11, s11, 0
	s_add_u32 s76, s76, 0x18000
	s_addc_u32 s77, s77, 0
	s_add_u32 s78, s78, 0x18000
	s_addc_u32 s79, s79, 0
	s_add_u32 s80, s80, 0x18000
	s_addc_u32 s81, s81, 0
	s_add_u32 s12, s12, 0x18000
	s_addc_u32 s13, s13, 0
	s_add_u32 s14, s14, 0x18000
	s_addc_u32 s15, s15, 0
	s_add_u32 s16, s16, 0x18000
	s_addc_u32 s17, s17, 0
	s_add_u32 s20, s20, 0x18000
	s_addc_u32 s21, s21, 0
	s_add_u32 s2, s2, 0x18000
	s_addc_u32 s3, s3, 0
	s_add_u32 s22, s22, 0x18000
	s_addc_u32 s23, s23, 0
	s_add_u32 s0, s0, 0x18000
	s_addc_u32 s1, s1, 0
	s_add_u32 s24, s24, 0x18000
	s_addc_u32 s25, s25, 0
	s_add_u32 s56, s56, 0x18000
	s_addc_u32 s57, s57, 0
	s_add_u32 s58, s58, 0x18000
	s_addc_u32 s59, s59, 0
	s_add_u32 s60, s60, 0x18000
	s_addc_u32 s61, s61, 0
	s_add_u32 s62, s62, 0x18000
	s_addc_u32 s63, s63, 0
	s_add_u32 s64, s64, 0x18000
	s_addc_u32 s65, s65, 0
	s_add_u32 s66, s66, 0x18000
	s_addc_u32 s67, s67, 0
	s_add_u32 s68, s68, 0x18000
	s_addc_u32 s69, s69, 0
	s_cmp_ge_i32 s5, s88
	s_waitcnt vmcnt(0)
	v_fmac_f32_e32 v183, v77, v182
	v_fmac_f32_e32 v185, v183, v184
	v_fmac_f32_e32 v187, v185, v186
	v_fmac_f32_e32 v189, v187, v188
	v_fmac_f32_e32 v191, v189, v190
	v_fmac_f32_e32 v193, v191, v192
	v_fmac_f32_e32 v195, v193, v194
	v_fmac_f32_e32 v197, v195, v196
	v_fmac_f32_e32 v199, v197, v198
	v_fmac_f32_e32 v201, v199, v200
	v_fmac_f32_e32 v203, v201, v202
	v_fmac_f32_e32 v205, v203, v204
	v_fmac_f32_e32 v207, v205, v206
	v_fmac_f32_e32 v209, v207, v208
	v_fmac_f32_e32 v211, v209, v210
	v_fmac_f32_e32 v213, v211, v212
	v_mov_b32_e32 v77, v213
	s_cbranch_scc0 .LBB0_521
	v_readlane_b32 s36, v253, 50
	v_readlane_b32 s37, v253, 51
	v_readlane_b32 s38, v253, 52
	v_readlane_b32 s39, v253, 53
	v_readlane_b32 s40, v253, 54
	v_readlane_b32 s41, v253, 55
	v_readlane_b32 s42, v253, 56
	v_readlane_b32 s43, v253, 57
	v_readlane_b32 s46, v253, 60
	v_readlane_b32 s47, v253, 61
	v_readlane_b32 s48, v253, 62
	v_readlane_b32 s49, v253, 63
	v_readlane_b32 s50, v255, 0
	v_readlane_b32 s51, v255, 1
	v_readlane_b32 s44, v253, 58
	v_readlane_b32 s45, v253, 59

.LBB0_761:
	s_cmpk_gt_u32 s20, 0x37f
	s_cbranch_scc1 .LBB0_758
	s_cmpk_gt_u32 s20, 0x27f
	s_cbranch_scc1 .Lp5_f32
	v_lshl_add_u64 v[64:65], v[116:117], 0, v[118:119]
	v_lshl_add_u64 v[68:69], v[116:117], 0, v[120:121]
	v_lshl_add_u64 v[72:73], v[116:117], 0, v[122:123]
	v_lshl_add_u64 v[76:77], v[116:117], 0, v[124:125]
	global_load_dwordx4 v[64:67], v[64:65], off
	global_load_dwordx4 v[68:71], v[68:69], off
	global_load_dwordx4 v[72:75], v[72:73], off
	global_load_dwordx4 v[76:79], v[76:77], off
	s_branch .LBB0_757
.Lp5_f32:
	v_lshl_add_u64 v[216:217], v[128:129], 0, v[136:137]
	v_lshl_add_u64 v[218:219], v[128:129], 0, v[134:135]
	v_lshl_add_u64 v[220:221], v[128:129], 0, v[132:133]
	v_lshl_add_u64 v[222:223], v[128:129], 0, v[126:127]
	global_load_dwordx4 v[184:187], v[216:217], off
	global_load_dwordx4 v[188:191], v[216:217], off offset:16
	global_load_dwordx4 v[192:195], v[218:219], off
	global_load_dwordx4 v[196:199], v[218:219], off offset:16
	global_load_dwordx4 v[200:203], v[220:221], off
	global_load_dwordx4 v[204:207], v[220:221], off offset:16
	global_load_dwordx4 v[208:211], v[222:223], off
	global_load_dwordx4 v[212:215], v[222:223], off offset:16
	s_waitcnt vmcnt(0)
	v_cvt_pk_bf16_f32 v64, v184, v185
	v_cvt_pk_bf16_f32 v65, v186, v187
	v_cvt_pk_bf16_f32 v66, v188, v189
	v_cvt_pk_bf16_f32 v67, v190, v191
	v_cvt_pk_bf16_f32 v68, v192, v193
	v_cvt_pk_bf16_f32 v69, v194, v195
	v_cvt_pk_bf16_f32 v70, v196, v197
	v_cvt_pk_bf16_f32 v71, v198, v199
	v_cvt_pk_bf16_f32 v72, v200, v201
	v_cvt_pk_bf16_f32 v73, v202, v203
	v_cvt_pk_bf16_f32 v74, v204, v205
	v_cvt_pk_bf16_f32 v75, v206, v207
	v_cvt_pk_bf16_f32 v76, v208, v209
	v_cvt_pk_bf16_f32 v77, v210, v211
	v_cvt_pk_bf16_f32 v78, v212, v213
	v_cvt_pk_bf16_f32 v79, v214, v215
	s_branch .LBB0_757
